# attention DQK128 loop: K fragments read 3 MFMAs ahead into rotating registers, second-half exps moved into the QK chain shadows, V reads before cvt block
# speedup vs baseline: 1.0056x; 1.0056x over previous
; #define SBAR() __builtin_amdgcn_sched_barrier(0)
; #define DMA_K(t, buf) do { const char* kb_ = (const char*)Kh + (size_t)(t) * TILEB; \
;         glds16(kb_ + ksrc[0], (unsigned)__builtin_amdgcn_readfirstlane(lds0 + OFF_K + (buf) * SHM_K + (DQK == 128 ? widu * 2048 : widu * 1024))); \
;         if (DQK == 128) glds16(kb_ + ksrc[1], (unsigned)__builtin_amdgcn_readfirstlane(lds0 + OFF_K + (buf) * SHM_K + widu * 2048 + 1024)); } while (0)
; #define DMA_V(t, buf) do { const char* vb_ = (const char*)Vh + (size_t)(t) * TILEB; \
;         glds16(vb_ + vsrc[0], (unsigned)__builtin_amdgcn_readfirstlane(lds0 + (buf) * SHM_V + widu * 2048)); \
;         glds16(vb_ + vsrc[1], (unsigned)__builtin_amdgcn_readfirstlane(lds0 + (buf) * SHM_V + widu * 2048 + 1024)); } while (0)
; #define EXPH(P) do { _Pragma("unroll") for (int r = 0; r < 16; ++r) P[r] = __builtin_amdgcn_exp2f(P[r]); } while (0)
; template <int DQK, int NREG> __device__ __forceinline__ void qkt_mix(f32x16& p0, f32x16& p1, const char* Ks, const bf16x8* qr, const char* qs, int r32, int hi) {
;     p0 = f32x16{}; p1 = f32x16{};
; #pragma unroll
;     for (int d0 = 0; d0 < DQK / 16; ++d0) { const int cb = (d0 * 16 + hi * 8) * 2, ci = 0;
;         const bf16x8 b0 = *reinterpret_cast<const bf16x8*>(Ks + kswz<DQK>(r32, cb) + ci);
;         const bf16x8 b1 = *reinterpret_cast<const bf16x8*>(Ks + kswz<DQK>(r32, cb) + ci + 32 * (DQK * 2));
;         bf16x8 q; if (d0 < NREG) q = qr[d0]; else q = *reinterpret_cast<const bf16x8*>(qs + (d0 - NREG) * 1024);
;         p0 = __builtin_amdgcn_mfma_f32_32x32x16_bf16(b0, q, p0, 0, 0, 0);
;         p1 = __builtin_amdgcn_mfma_f32_32x32x16_bf16(b1, q, p1, 0, 0, 0); }
; }
;     ...
;         DMA_K(k + 1, 0); DMA_V(k, 1); SBAR();
;         if (isY) { EXPH(pA0); }
;         SBAR(); qkt_mix<DQK, NREG>(pB0, pB1, K_lds + SHM_K, qr, qs, r32, hi);
;         finishSM<true>(pA0, pA1, dummy_a, l_reg, pa0, pa1, pa2, pa3); SBAR();
;         pv_d0(o, vb0, pa0, pa1, pa2, pa3);
.LBB0_529:
	s_add_u32 s76, s44, 0xfffa0000
	s_addc_u32 s77, s45, -1
	v_lshl_add_u64 v[80:81], s[76:77], 0, v[160:161]
	s_mov_b32 s1, m0
	s_mov_b32 m0, s53
	s_nop 0
	global_load_lds_dwordx4 v[80:81], off
	s_mov_b32 m0, s1
	v_lshl_add_u64 v[80:81], s[76:77], 0, v[162:163]
	s_mov_b32 s1, m0
	s_mov_b32 m0, s54
	s_nop 0
	global_load_lds_dwordx4 v[80:81], off
	s_mov_b32 m0, s1
	s_cmp_lg_u32 0, -1
	s_cselect_b32 s1, 0, 0
	v_lshl_add_u64 v[200:201], s[44:45], 0, v[164:165]
	s_add_i32 s1, s1, s52
	v_lshl_add_u64 v[80:81], v[200:201], 0, s[20:21]
	s_add_i32 s75, s1, 0x4000
	s_mov_b32 s76, m0
	s_mov_b32 m0, s75
	s_nop 0
	global_load_lds_dwordx4 v[80:81], off
	s_mov_b32 m0, s76
	v_lshl_add_u64 v[80:81], v[200:201], 0, s[22:23]
	s_addk_i32 s1, 0x4400
	s_mov_b32 s75, m0
	s_mov_b32 m0, s1
	s_nop 0
	global_load_lds_dwordx4 v[80:81], off
	s_mov_b32 m0, s75
	ds_read_b128 v[80:83], v231 offset:49152
	ds_read_b128 v[156:159], v231 offset:57344
	ds_read_b128 v[240:243], v232 offset:49152
	ds_read_b128 v[152:155], v232 offset:57344
	ds_read_b128 v[244:247], v233 offset:49152
	ds_read_b128 v[148:151], v233 offset:57344
	ds_read_b128 v[248:251], v234 offset:49152
	ds_read_b128 v[144:147], v234 offset:57344
	s_waitcnt lgkmcnt(7)
	v_mfma_f32_32x32x16_bf16 v[80:95], v[80:83], v[116:119], 0
	s_waitcnt lgkmcnt(5)
	v_mfma_f32_32x32x16_bf16 v[80:95], v[240:243], v[112:115], v[80:95]
	ds_read_b128 v[240:243], v235 offset:49152
	ds_read_b128 v[140:143], v235 offset:57344
	v_exp_f32_e32 v217, v64
	v_exp_f32_e32 v215, v65
	s_waitcnt lgkmcnt(5)
	v_mfma_f32_32x32x16_bf16 v[80:95], v[244:247], v[108:111], v[80:95]
	ds_read_b128 v[244:247], v236 offset:49152
	ds_read_b128 v[136:139], v236 offset:57344
	v_exp_f32_e32 v216, v66
	v_exp_f32_e32 v214, v67
	s_waitcnt lgkmcnt(5)
	v_mfma_f32_32x32x16_bf16 v[80:95], v[248:251], v[104:107], v[80:95]
	ds_read_b128 v[248:251], v237 offset:49152
	ds_read_b128 v[124:127], v229
	ds_read_b128 v[132:135], v237 offset:57344
	v_exp_f32_e32 v213, v68
	v_exp_f32_e32 v211, v69
	s_waitcnt lgkmcnt(6)
	v_mfma_f32_32x32x16_bf16 v[80:95], v[240:243], v[100:103], v[80:95]
	ds_read_b128 v[240:243], v238 offset:49152
	ds_read_b128 v[120:123], v229 offset:1024
	ds_read_b128 v[128:131], v238 offset:57344
	v_exp_f32_e32 v212, v70
	v_exp_f32_e32 v210, v71
	s_waitcnt lgkmcnt(7)
	v_mfma_f32_32x32x16_bf16 v[80:95], v[244:247], v[96:99], v[80:95]
	v_exp_f32_e32 v209, v72
	v_exp_f32_e32 v207, v73
	v_exp_f32_e32 v208, v74
	s_waitcnt lgkmcnt(4)
	v_mfma_f32_32x32x16_bf16 v[80:95], v[248:251], v[124:127], v[80:95]
	v_exp_f32_e32 v206, v75
	v_exp_f32_e32 v205, v76
	v_exp_f32_e32 v203, v77
	s_waitcnt lgkmcnt(1)
	v_mfma_f32_32x32x16_bf16 v[80:95], v[240:243], v[120:123], v[80:95]
	v_exp_f32_e32 v204, v78
	v_exp_f32_e32 v202, v79
	ds_read_b64_tr_b16 v[184:185], v228 offset:0
	ds_read_b64_tr_b16 v[186:187], v228 offset:0x800
	ds_read_b64_tr_b16 v[188:189], v228 offset:0x1000
	ds_read_b64_tr_b16 v[190:191], v228 offset:0x1800
	ds_read_b64_tr_b16 v[192:193], v228 offset:0x2000
	ds_read_b64_tr_b16 v[194:195], v228 offset:0x2800
	ds_read_b64_tr_b16 v[196:197], v228 offset:0x3000
	ds_read_b64_tr_b16 v[198:199], v228 offset:0x3800
	v_cvt_pk_bf16_f32 v64, v183, v181
	v_cvt_pk_bf16_f32 v65, v182, v180
	v_cvt_pk_bf16_f32 v66, v179, v177
	v_cvt_pk_bf16_f32 v67, v178, v176
	v_cvt_pk_bf16_f32 v68, v175, v173
	v_cvt_pk_bf16_f32 v69, v174, v172
	v_cvt_pk_bf16_f32 v70, v171, v169
	v_cvt_pk_bf16_f32 v71, v170, v168
	v_cvt_pk_bf16_f32 v72, v217, v215
	v_cvt_pk_bf16_f32 v73, v216, v214
	v_cvt_pk_bf16_f32 v74, v213, v211
	v_cvt_pk_bf16_f32 v75, v212, v210
	v_cvt_pk_bf16_f32 v76, v209, v207
	v_cvt_pk_bf16_f32 v77, v208, v206
	v_cvt_pk_bf16_f32 v78, v205, v203
	v_cvt_pk_bf16_f32 v79, v204, v202
	s_nop 0
	v_permlane32_swap_b32_e32 v64, v66
	v_permlane32_swap_b32_e32 v65, v67
	v_permlane32_swap_b32_e32 v68, v70
	v_permlane32_swap_b32_e32 v69, v71
	v_permlane32_swap_b32_e32 v72, v74
	v_permlane32_swap_b32_e32 v73, v75
	v_permlane32_swap_b32_e32 v76, v78
	v_permlane32_swap_b32_e32 v77, v79
	s_waitcnt lgkmcnt(0)
	s_nop 0
	v_mfma_f32_32x32x16_bf16 v[0:15], v[64:67], v[184:187], v[0:15]
	ds_read_b64_tr_b16 v[184:185], v228 offset:0x200
	ds_read_b64_tr_b16 v[186:187], v228 offset:0xa00
	v_mfma_f32_32x32x16_bf16 v[0:15], v[68:71], v[188:191], v[0:15]
	ds_read_b64_tr_b16 v[188:189], v228 offset:0x1200
	ds_read_b64_tr_b16 v[190:191], v228 offset:0x1a00
	v_mfma_f32_32x32x16_bf16 v[0:15], v[72:75], v[192:195], v[0:15]
	ds_read_b64_tr_b16 v[192:193], v228 offset:0x2200
	ds_read_b64_tr_b16 v[194:195], v228 offset:0x2a00
	ds_read_b64_tr_b16 v[240:241], v228 offset:0x3200
	ds_read_b64_tr_b16 v[242:243], v228 offset:0x3a00
	s_waitcnt lgkmcnt(0)
	v_mfma_f32_32x32x16_bf16 v[0:15], v[76:79], v[196:199], v[0:15]
	v_mfma_f32_32x32x16_bf16 v[16:31], v[64:67], v[184:187], v[16:31]
	ds_read_b64_tr_b16 v[184:185], v228 offset:0x400
	ds_read_b64_tr_b16 v[186:187], v228 offset:0xc00
	v_mfma_f32_32x32x16_bf16 v[16:31], v[68:71], v[188:191], v[16:31]
	ds_read_b64_tr_b16 v[188:189], v228 offset:0x1400
	ds_read_b64_tr_b16 v[190:191], v228 offset:0x1c00
	v_mfma_f32_32x32x16_bf16 v[16:31], v[72:75], v[192:195], v[16:31]
	ds_read_b64_tr_b16 v[192:193], v228 offset:0x2400
	ds_read_b64_tr_b16 v[194:195], v228 offset:0x2c00
	ds_read_b64_tr_b16 v[196:197], v228 offset:0x3400
	ds_read_b64_tr_b16 v[198:199], v228 offset:0x3c00
	s_waitcnt lgkmcnt(0)
; #define SBAR() __builtin_amdgcn_sched_barrier(0)
; #define DMA_K(t, buf) do { const char* kb_ = (const char*)Kh + (size_t)(t) * TILEB; \
;         glds16(kb_ + ksrc[0], (unsigned)__builtin_amdgcn_readfirstlane(lds0 + OFF_K + (buf) * SHM_K + (DQK == 128 ? widu * 2048 : widu * 1024))); \
;         if (DQK == 128) glds16(kb_ + ksrc[1], (unsigned)__builtin_amdgcn_readfirstlane(lds0 + OFF_K + (buf) * SHM_K + widu * 2048 + 1024)); } while (0)
; #define DMA_V(t, buf) do { const char* vb_ = (const char*)Vh + (size_t)(t) * TILEB; \
;         glds16(vb_ + vsrc[0], (unsigned)__builtin_amdgcn_readfirstlane(lds0 + (buf) * SHM_V + widu * 2048)); \
;         glds16(vb_ + vsrc[1], (unsigned)__builtin_amdgcn_readfirstlane(lds0 + (buf) * SHM_V + widu * 2048 + 1024)); } while (0)
; #define WBAR0() do { asm volatile("s_waitcnt vmcnt(0)" ::: "memory"); __syncthreads(); } while (0)
; #define EXPH(P) do { _Pragma("unroll") for (int r = 0; r < 16; ++r) P[r] = __builtin_amdgcn_exp2f(P[r]); } while (0)
; template <bool FAST> __device__ __forceinline__ void finishSM(f32x16& p0, f32x16& p1, float alpha, float& l_reg, bf16x8& pa0, bf16x8& pa1, bf16x8& pa2, bf16x8& pa3) {
;     ...
;     if (FAST) { float s0 = 0.f, s1 = 0.f, s2 = 0.f, s3 = 0.f;
; #pragma unroll
;         for (int r = 0; r < 16; r += 4) { s0 += p0[r] + p1[r]; s1 += p0[r + 1] + p1[r + 1]; s2 += p0[r + 2] + p1[r + 2]; s3 += p0[r + 3] + p1[r + 3]; }
;         ps = (s0 + s1) + (s2 + s3); }
;     else {
; #pragma unroll
;     for (int r = 0; r < 16; ++r) ps += p0[r];
; #pragma unroll
;     for (int r = 0; r < 16; ++r) ps += p1[r];
;     }
;     if (FAST) { SBAR(); l_reg += ps; }
;     ...
;         pv_d0(o, vb0, pa0, pa1, pa2, pa3);
;         if (!isY) { EXPH(pB0); }
;         WBAR0();
;         DMA_K(k + 2, 1); DMA_V(k + 1, 0); SBAR();
;         if (isY) { EXPH(pB0); }
;         SBAR(); qkt_mix<DQK, NREG>(pA0, pA1, K_lds, qr, qs, r32, hi);
;         finishSM<true>(pB0, pB1, dummy_a, l_reg, pa0, pa1, pa2, pa3); SBAR();
	v_mfma_f32_32x32x16_bf16 v[16:31], v[76:79], v[240:243], v[16:31]
	v_mfma_f32_32x32x16_bf16 v[32:47], v[64:67], v[184:187], v[32:47]
	ds_read_b64_tr_b16 v[184:185], v228 offset:0x600
	ds_read_b64_tr_b16 v[186:187], v228 offset:0xe00
	v_mfma_f32_32x32x16_bf16 v[32:47], v[68:71], v[188:191], v[32:47]
	ds_read_b64_tr_b16 v[188:189], v228 offset:0x1600
	ds_read_b64_tr_b16 v[190:191], v228 offset:0x1e00
	v_mfma_f32_32x32x16_bf16 v[32:47], v[72:75], v[192:195], v[32:47]
	ds_read_b64_tr_b16 v[192:193], v228 offset:0x2600
	ds_read_b64_tr_b16 v[194:195], v228 offset:0x2e00
	ds_read_b64_tr_b16 v[240:241], v228 offset:0x3600
	ds_read_b64_tr_b16 v[242:243], v228 offset:0x3e00
	s_waitcnt lgkmcnt(0)
	v_mfma_f32_32x32x16_bf16 v[32:47], v[76:79], v[196:199], v[32:47]
	v_mfma_f32_32x32x16_bf16 v[48:63], v[64:67], v[184:187], v[48:63]
	v_exp_f32_e32 v199, v80
	v_exp_f32_e32 v197, v81
	v_exp_f32_e32 v198, v82
	v_exp_f32_e32 v196, v83
	v_pk_add_f32 v[80:81], v[182:183], v[216:217]
	v_pk_add_f32 v[82:83], v[180:181], v[214:215]
	v_pk_add_f32 v[80:81], v[80:81], 0 op_sel_hi:[1,0]
	v_mfma_f32_32x32x16_bf16 v[48:63], v[68:71], v[188:191], v[48:63]
	v_add_f32_e64 v82, v82, 0
	v_add_f32_e64 v83, v83, 0
	v_exp_f32_e32 v191, v88
	v_exp_f32_e32 v189, v89
	v_exp_f32_e32 v190, v90
	v_exp_f32_e32 v188, v91
	v_pk_add_f32 v[88:89], v[174:175], v[208:209]
	v_pk_add_f32 v[90:91], v[172:173], v[206:207]
	v_mfma_f32_32x32x16_bf16 v[48:63], v[72:75], v[192:195], v[48:63]
	v_exp_f32_e32 v195, v84
	v_exp_f32_e32 v193, v85
	v_exp_f32_e32 v194, v86
	v_exp_f32_e32 v192, v87
	v_pk_add_f32 v[84:85], v[178:179], v[212:213]
	v_pk_add_f32 v[86:87], v[176:177], v[210:211]
	v_pk_add_f32 v[80:81], v[84:85], v[80:81]
	v_mfma_f32_32x32x16_bf16 v[48:63], v[76:79], v[240:243], v[48:63]
	v_add_f32_e64 v82, v86, v82
	v_add_f32_e64 v83, v87, v83
	v_exp_f32_e32 v187, v92
	v_exp_f32_e32 v185, v93
	v_exp_f32_e32 v186, v94
	v_exp_f32_e32 v184, v95
	v_pk_add_f32 v[92:93], v[170:171], v[204:205]
	v_pk_add_f32 v[94:95], v[168:169], v[202:203]
	v_mfma_f32_32x32x16_bf16 v[64:79], v[156:159], v[116:119], 0
	v_add_f32_e64 v80, v88, v80
	v_add_f32_e64 v81, v89, v81
	v_add_f32_e64 v82, v90, v82
	v_add_f32_e64 v83, v91, v83
	v_add_f32_e64 v80, v92, v80
	v_add_f32_e64 v81, v93, v81
	v_pk_add_f32 v[82:83], v[94:95], v[82:83]
	s_waitcnt vmcnt(0)
	s_waitcnt lgkmcnt(0)
	v_pk_add_f32 v[80:81], v[82:83], v[80:81]
	v_mfma_f32_32x32x16_bf16 v[64:79], v[152:155], v[112:115], v[64:79]
	v_add_f32_e32 v216, v80, v81
	s_barrier
	v_lshl_add_u64 v[80:81], s[44:45], 0, v[160:161]
	s_mov_b32 s1, m0
	s_mov_b32 m0, s73
	s_nop 0
	global_load_lds_dwordx4 v[80:81], off
	s_mov_b32 m0, s1
	v_lshl_add_u64 v[80:81], s[44:45], 0, v[162:163]
	s_mov_b32 s1, m0
	s_mov_b32 m0, s74
	s_nop 0
	global_load_lds_dwordx4 v[80:81], off
	s_mov_b32 m0, s1
	v_mfma_f32_32x32x16_bf16 v[64:79], v[148:151], v[108:111], v[64:79]
	v_lshl_add_u64 v[80:81], v[200:201], 0, s[26:27]
	s_mov_b32 s1, m0
	s_mov_b32 m0, s72
	s_nop 0
	global_load_lds_dwordx4 v[80:81], off
	s_mov_b32 m0, s1
	v_lshl_add_u64 v[80:81], v[200:201], 0, s[28:29]
	s_mov_b32 s1, m0
	s_mov_b32 m0, s0
	s_nop 0
	global_load_lds_dwordx4 v[80:81], off
	s_mov_b32 m0, s1
	v_mfma_f32_32x32x16_bf16 v[64:79], v[144:147], v[104:107], v[64:79]
	v_mfma_f32_32x32x16_bf16 v[64:79], v[140:143], v[100:103], v[64:79]
	v_mfma_f32_32x32x16_bf16 v[64:79], v[136:139], v[96:99], v[64:79]
	v_mfma_f32_32x32x16_bf16 v[64:79], v[132:135], v[124:127], v[64:79]
	v_mfma_f32_32x32x16_bf16 v[64:79], v[128:131], v[120:123], v[64:79]
	ds_read_b128 v[80:83], v231 offset:32768
	ds_read_b128 v[148:151], v231 offset:40960
	ds_read_b128 v[240:243], v232 offset:32768
	ds_read_b128 v[152:155], v232 offset:40960
	ds_read_b128 v[244:247], v233 offset:32768
	ds_read_b128 v[156:159], v233 offset:40960
	ds_read_b128 v[248:251], v234 offset:32768
	ds_read_b128 v[144:147], v234 offset:40960
	s_waitcnt lgkmcnt(7)
	v_mfma_f32_32x32x16_bf16 v[80:95], v[80:83], v[116:119], 0
	s_waitcnt lgkmcnt(5)
	v_mfma_f32_32x32x16_bf16 v[80:95], v[240:243], v[112:115], v[80:95]
	ds_read_b128 v[240:243], v235 offset:32768
	ds_read_b128 v[140:143], v235 offset:40960
	s_waitcnt lgkmcnt(5)
	v_mfma_f32_32x32x16_bf16 v[80:95], v[244:247], v[108:111], v[80:95]
	ds_read_b128 v[244:247], v236 offset:32768
	ds_read_b128 v[136:139], v236 offset:40960
	v_exp_f32_e32 v215, v64
	v_exp_f32_e32 v213, v65
	s_waitcnt lgkmcnt(5)
	v_mfma_f32_32x32x16_bf16 v[80:95], v[248:251], v[104:107], v[80:95]
	ds_read_b128 v[248:251], v237 offset:32768
	ds_read_b128 v[124:127], v229
	ds_read_b128 v[128:131], v237 offset:40960
	v_exp_f32_e32 v214, v66
	v_exp_f32_e32 v212, v67
	s_waitcnt lgkmcnt(6)
	v_mfma_f32_32x32x16_bf16 v[80:95], v[240:243], v[100:103], v[80:95]
	ds_read_b128 v[240:243], v238 offset:32768
	ds_read_b128 v[120:123], v229 offset:1024
	ds_read_b128 v[132:135], v238 offset:40960
	v_exp_f32_e32 v211, v68
	v_exp_f32_e32 v209, v69
	v_exp_f32_e32 v210, v70
	s_waitcnt lgkmcnt(7)
	v_mfma_f32_32x32x16_bf16 v[80:95], v[244:247], v[96:99], v[80:95]
	v_exp_f32_e32 v208, v71
	v_exp_f32_e32 v207, v72
	v_exp_f32_e32 v205, v73
	s_waitcnt lgkmcnt(4)
	v_mfma_f32_32x32x16_bf16 v[80:95], v[248:251], v[124:127], v[80:95]
	v_exp_f32_e32 v206, v74
	v_exp_f32_e32 v204, v75
	v_exp_f32_e32 v203, v76
	s_waitcnt lgkmcnt(1)
; #define SBAR() __builtin_amdgcn_sched_barrier(0)
; #define WBAR0() do { asm volatile("s_waitcnt vmcnt(0)" ::: "memory"); __syncthreads(); } while (0)
; #define EXPH(P) do { _Pragma("unroll") for (int r = 0; r < 16; ++r) P[r] = __builtin_amdgcn_exp2f(P[r]); } while (0)
; template <int D0> __device__ __forceinline__ void pv_one(f32x16& od, int vb, bf16x8 pa0, bf16x8 pa1, bf16x8 pa2, bf16x8 pa3) {
;     const s16x4 l0 = tr_read<v_rd_off(D0, 0, 0)>(vb), h0 = tr_read<v_rd_off(D0, 0, 1)>(vb), l1 = tr_read<v_rd_off(D0, 1, 0)>(vb), h1 = tr_read<v_rd_off(D0, 1, 1)>(vb);
;     const s16x4 l2 = tr_read<v_rd_off(D0, 2, 0)>(vb), h2 = tr_read<v_rd_off(D0, 2, 1)>(vb), l3 = tr_read<v_rd_off(D0, 3, 0)>(vb), h3 = tr_read<v_rd_off(D0, 3, 1)>(vb);
;     asm volatile("s_waitcnt lgkmcnt(0)" ::: "memory"); SBAR();
;     ...
;     od = __builtin_amdgcn_mfma_f32_32x32x16_bf16(pa0, PK(l0, h0), od, 0, 0, 0);
;     od = __builtin_amdgcn_mfma_f32_32x32x16_bf16(pa1, PK(l1, h1), od, 0, 0, 0);
;     od = __builtin_amdgcn_mfma_f32_32x32x16_bf16(pa2, PK(l2, h2), od, 0, 0, 0);
;     od = __builtin_amdgcn_mfma_f32_32x32x16_bf16(pa3, PK(l3, h3), od, 0, 0, 0);
;     ...
; }
; __device__ __forceinline__ void pv_d0(f32x16* o, int vb, bf16x8 pa0, bf16x8 pa1, bf16x8 pa2, bf16x8 pa3) {
;     pv_one<0>(o[0], vb, pa0, pa1, pa2, pa3); pv_one<1>(o[1], vb, pa0, pa1, pa2, pa3); pv_one<2>(o[2], vb, pa0, pa1, pa2, pa3); pv_one<3>(o[3], vb, pa0, pa1, pa2, pa3);
;     ...
;         finishSM<true>(pB0, pB1, dummy_a, l_reg, pa0, pa1, pa2, pa3); SBAR();
;         pv_d0(o, vb0 + SHM_V, pa0, pa1, pa2, pa3);
;         if (!isY) { EXPH(pA0); }
;         WBAR0();
	v_mfma_f32_32x32x16_bf16 v[80:95], v[240:243], v[120:123], v[80:95]
	v_exp_f32_e32 v201, v77
	v_exp_f32_e32 v202, v78
	v_exp_f32_e32 v200, v79
	ds_read_b64_tr_b16 v[68:69], v227 offset:0
	ds_read_b64_tr_b16 v[70:71], v227 offset:0x800
	ds_read_b64_tr_b16 v[72:73], v227 offset:0x1000
	ds_read_b64_tr_b16 v[74:75], v227 offset:0x1800
	ds_read_b64_tr_b16 v[76:77], v227 offset:0x2000
	ds_read_b64_tr_b16 v[78:79], v227 offset:0x2800
	ds_read_b64_tr_b16 v[180:181], v227 offset:0x3000
	ds_read_b64_tr_b16 v[182:183], v227 offset:0x3800
	v_cvt_pk_bf16_f32 v64, v199, v197
	v_cvt_pk_bf16_f32 v65, v198, v196
	v_cvt_pk_bf16_f32 v66, v195, v193
	v_cvt_pk_bf16_f32 v67, v194, v192
	v_cvt_pk_bf16_f32 v168, v191, v189
	v_cvt_pk_bf16_f32 v169, v190, v188
	v_cvt_pk_bf16_f32 v170, v187, v185
	v_cvt_pk_bf16_f32 v171, v186, v184
	v_cvt_pk_bf16_f32 v172, v215, v213
	v_cvt_pk_bf16_f32 v173, v214, v212
	v_cvt_pk_bf16_f32 v174, v211, v209
	v_cvt_pk_bf16_f32 v175, v210, v208
	v_cvt_pk_bf16_f32 v176, v207, v205
	v_cvt_pk_bf16_f32 v177, v206, v204
	v_cvt_pk_bf16_f32 v178, v203, v201
	v_cvt_pk_bf16_f32 v179, v202, v200
	s_nop 0
	v_permlane32_swap_b32_e32 v64, v66
	v_permlane32_swap_b32_e32 v65, v67
	v_permlane32_swap_b32_e32 v168, v170
	v_permlane32_swap_b32_e32 v169, v171
	v_permlane32_swap_b32_e32 v172, v174
	v_permlane32_swap_b32_e32 v173, v175
	v_permlane32_swap_b32_e32 v176, v178
	v_permlane32_swap_b32_e32 v177, v179
	s_waitcnt lgkmcnt(0)
	s_nop 0
	v_mfma_f32_32x32x16_bf16 v[0:15], v[64:67], v[68:71], v[0:15]
	ds_read_b64_tr_b16 v[68:69], v227 offset:0x200
	ds_read_b64_tr_b16 v[70:71], v227 offset:0xa00
	v_mfma_f32_32x32x16_bf16 v[0:15], v[168:171], v[72:75], v[0:15]
	ds_read_b64_tr_b16 v[72:73], v227 offset:0x1200
	ds_read_b64_tr_b16 v[74:75], v227 offset:0x1a00
	v_mfma_f32_32x32x16_bf16 v[0:15], v[172:175], v[76:79], v[0:15]
	ds_read_b64_tr_b16 v[76:77], v227 offset:0x2200
	ds_read_b64_tr_b16 v[78:79], v227 offset:0x2a00
	ds_read_b64_tr_b16 v[240:241], v227 offset:0x3200
	ds_read_b64_tr_b16 v[242:243], v227 offset:0x3a00
	s_waitcnt lgkmcnt(0)
	v_mfma_f32_32x32x16_bf16 v[0:15], v[176:179], v[180:183], v[0:15]
	v_mfma_f32_32x32x16_bf16 v[16:31], v[64:67], v[68:71], v[16:31]
	ds_read_b64_tr_b16 v[68:69], v227 offset:0x400
	ds_read_b64_tr_b16 v[70:71], v227 offset:0xc00
	v_mfma_f32_32x32x16_bf16 v[16:31], v[168:171], v[72:75], v[16:31]
	ds_read_b64_tr_b16 v[72:73], v227 offset:0x1400
	ds_read_b64_tr_b16 v[74:75], v227 offset:0x1c00
	v_mfma_f32_32x32x16_bf16 v[16:31], v[172:175], v[76:79], v[16:31]
	ds_read_b64_tr_b16 v[76:77], v227 offset:0x2400
	ds_read_b64_tr_b16 v[78:79], v227 offset:0x2c00
	ds_read_b64_tr_b16 v[180:181], v227 offset:0x3400
	ds_read_b64_tr_b16 v[182:183], v227 offset:0x3c00
	s_waitcnt lgkmcnt(0)
	v_mfma_f32_32x32x16_bf16 v[16:31], v[176:179], v[240:243], v[16:31]
	v_mfma_f32_32x32x16_bf16 v[32:47], v[64:67], v[68:71], v[32:47]
	ds_read_b64_tr_b16 v[68:69], v227 offset:0x600
	ds_read_b64_tr_b16 v[70:71], v227 offset:0xe00
	ds_read_b64_tr_b16 v[240:241], v227 offset:0x1600
	ds_read_b64_tr_b16 v[242:243], v227 offset:0x1e00
	ds_read_b64_tr_b16 v[244:245], v227 offset:0x2600
	ds_read_b64_tr_b16 v[246:247], v227 offset:0x2e00
	ds_read_b64_tr_b16 v[248:249], v227 offset:0x3600
	v_mfma_f32_32x32x16_bf16 v[32:47], v[168:171], v[72:75], v[32:47]
	ds_read_b64_tr_b16 v[250:251], v227 offset:0x3e00
	s_waitcnt lgkmcnt(0)
	v_mfma_f32_32x32x16_bf16 v[32:47], v[172:175], v[76:79], v[32:47]
	v_mfma_f32_32x32x16_bf16 v[32:47], v[176:179], v[180:183], v[32:47]
	v_mfma_f32_32x32x16_bf16 v[48:63], v[64:67], v[68:71], v[48:63]
	v_exp_f32_e32 v183, v80
	v_exp_f32_e32 v181, v81
	v_exp_f32_e32 v182, v82
	v_exp_f32_e32 v180, v83
	v_pk_add_f32 v[80:81], v[198:199], v[214:215]
	v_pk_add_f32 v[82:83], v[196:197], v[212:213]
	v_pk_add_f32 v[80:81], v[80:81], 0 op_sel_hi:[1,0]
	v_mfma_f32_32x32x16_bf16 v[64:79], v[148:151], v[116:119], 0
	v_add_f32_e64 v82, v82, 0
	v_add_f32_e64 v83, v83, 0
	s_add_i32 s55, s55, 2
	s_waitcnt vmcnt(0)
	s_add_u32 s44, s44, 0xc0000
	s_addc_u32 s45, s45, 0
	s_cmp_gt_u32 s55, 64
	s_waitcnt lgkmcnt(0)
	v_mfma_f32_32x32x16_bf16 v[64:79], v[152:155], v[112:115], v[64:79]
	s_barrier
	v_mfma_f32_32x32x16_bf16 v[64:79], v[156:159], v[108:111], v[64:79]
	v_mfma_f32_32x32x16_bf16 v[64:79], v[144:147], v[104:107], v[64:79]
	v_mfma_f32_32x32x16_bf16 v[64:79], v[140:143], v[100:103], v[64:79]
	v_add_f32_e32 v140, v230, v216
	v_mfma_f32_32x32x16_bf16 v[48:63], v[168:171], v[240:243], v[48:63]
	v_exp_f32_e32 v171, v92
	v_exp_f32_e32 v169, v93
	v_exp_f32_e32 v170, v94
	v_exp_f32_e32 v168, v95
	v_pk_add_f32 v[92:93], v[186:187], v[202:203]
	v_pk_add_f32 v[94:95], v[184:185], v[200:201]
	v_mfma_f32_32x32x16_bf16 v[64:79], v[136:139], v[96:99], v[64:79]
	v_mfma_f32_32x32x16_bf16 v[48:63], v[172:175], v[244:247], v[48:63]
	v_exp_f32_e32 v175, v88
	v_exp_f32_e32 v173, v89
	v_exp_f32_e32 v174, v90
	v_exp_f32_e32 v172, v91
	v_pk_add_f32 v[88:89], v[190:191], v[206:207]
	v_pk_add_f32 v[90:91], v[188:189], v[204:205]
	v_mfma_f32_32x32x16_bf16 v[64:79], v[128:131], v[124:127], v[64:79]
	v_mfma_f32_32x32x16_bf16 v[48:63], v[176:179], v[248:251], v[48:63]
	v_exp_f32_e32 v179, v84
	v_exp_f32_e32 v177, v85
	v_exp_f32_e32 v178, v86
	v_exp_f32_e32 v176, v87
	v_pk_add_f32 v[84:85], v[194:195], v[210:211]
	v_pk_add_f32 v[86:87], v[192:193], v[208:209]
	v_pk_add_f32 v[80:81], v[84:85], v[80:81]
	v_mfma_f32_32x32x16_bf16 v[64:79], v[132:135], v[120:123], v[64:79]
	v_add_f32_e64 v82, v86, v82
	v_add_f32_e64 v83, v87, v83
	v_add_f32_e64 v80, v88, v80
	v_add_f32_e64 v81, v89, v81
	v_add_f32_e64 v82, v90, v82
	v_add_f32_e64 v83, v91, v83
	v_pk_add_f32 v[80:81], v[92:93], v[80:81]
	v_pk_add_f32 v[82:83], v[94:95], v[82:83]
	s_nop 0
	v_pk_add_f32 v[80:81], v[82:83], v[80:81]
	s_nop 0
	v_add_f32_e32 v80, v80, v81
	v_add_f32_e32 v230, v140, v80
	s_cbranch_scc0 .LBB0_529
; #define SBAR() __builtin_amdgcn_sched_barrier(0)
; #define DMA_V(t, buf) do { const char* vb_ = (const char*)Vh + (size_t)(t) * TILEB; \
;         glds16(vb_ + vsrc[0], (unsigned)__builtin_amdgcn_readfirstlane(lds0 + (buf) * SHM_V + widu * 2048)); \
;         glds16(vb_ + vsrc[1], (unsigned)__builtin_amdgcn_readfirstlane(lds0 + (buf) * SHM_V + widu * 2048 + 1024)); } while (0)
; #define EXPH(P) do { _Pragma("unroll") for (int r = 0; r < 16; ++r) P[r] = __builtin_amdgcn_exp2f(P[r]); } while (0)
; template <int DQK, int NREG> __device__ __forceinline__ void qkt_mix(f32x16& p0, f32x16& p1, const char* Ks, const bf16x8* qr, const char* qs, int r32, int hi) {
;     p0 = f32x16{}; p1 = f32x16{};
; #pragma unroll
;     for (int d0 = 0; d0 < DQK / 16; ++d0) { const int cb = (d0 * 16 + hi * 8) * 2, ci = 0;
;         const bf16x8 b0 = *reinterpret_cast<const bf16x8*>(Ks + kswz<DQK>(r32, cb) + ci);
;         const bf16x8 b1 = *reinterpret_cast<const bf16x8*>(Ks + kswz<DQK>(r32, cb) + ci + 32 * (DQK * 2));
;         bf16x8 q; if (d0 < NREG) q = qr[d0]; else q = *reinterpret_cast<const bf16x8*>(qs + (d0 - NREG) * 1024);
;         p0 = __builtin_amdgcn_mfma_f32_32x32x16_bf16(b0, q, p0, 0, 0, 0);
;         p1 = __builtin_amdgcn_mfma_f32_32x32x16_bf16(b1, q, p1, 0, 0, 0); }
; }
;     ...
;     DMA_V(NT - 1, 1); SBAR();
;     if (isY) { EXPH(pA0); }
;     SBAR(); qkt_mix<DQK, NREG>(pB0, pB1, K_lds + SHM_K, qr, qs, r32, hi);
;     finishSM<true>(pA0, pA1, dummy_a, l_reg, pa0, pa1, pa2, pa3); SBAR();
;     pv_d0(o, vb0, pa0, pa1, pa2, pa3);
	s_cmp_lg_u32 0, -1
	s_cselect_b32 s0, 0, 0
	s_add_i32 s0, s0, s52
	v_lshl_add_u64 v[80:81], v[166:167], 0, s[38:39]
	s_add_i32 s1, s0, 0x4000
	s_mov_b32 s44, m0
	s_mov_b32 m0, s1
	s_nop 0
	global_load_lds_dwordx4 v[80:81], off
	s_mov_b32 m0, s44
	v_lshl_add_u64 v[80:81], v[166:167], 0, s[40:41]
	s_addk_i32 s0, 0x4400
	s_mov_b32 s1, m0
	s_mov_b32 m0, s0
	s_nop 0
	global_load_lds_dwordx4 v[80:81], off
	s_mov_b32 m0, s1
	ds_read_b128 v[80:83], v231 offset:49152
	ds_read_b128 v[144:147], v231 offset:57344
	ds_read_b128 v[120:123], v232 offset:49152
	ds_read_b128 v[148:151], v232 offset:57344
	s_waitcnt lgkmcnt(3)
	v_mfma_f32_32x32x16_bf16 v[80:95], v[80:83], v[116:119], 0
	s_waitcnt lgkmcnt(1)
	v_mfma_f32_32x32x16_bf16 v[80:95], v[120:123], v[112:115], v[80:95]
	ds_read_b128 v[120:123], v233 offset:49152
	ds_read_b128 v[152:155], v233 offset:57344
	s_waitcnt lgkmcnt(1)
	v_mfma_f32_32x32x16_bf16 v[80:95], v[120:123], v[108:111], v[80:95]
	ds_read_b128 v[120:123], v234 offset:49152
	ds_read_b128 v[156:159], v234 offset:57344
	s_waitcnt lgkmcnt(1)
	v_mfma_f32_32x32x16_bf16 v[80:95], v[120:123], v[104:107], v[80:95]
	ds_read_b128 v[120:123], v235 offset:49152
	ds_read_b128 v[140:143], v235 offset:57344
	s_waitcnt lgkmcnt(1)
	v_mfma_f32_32x32x16_bf16 v[80:95], v[120:123], v[100:103], v[80:95]
	ds_read_b128 v[120:123], v236 offset:49152
	ds_read_b128 v[136:139], v236 offset:57344
	s_waitcnt lgkmcnt(1)
	v_mfma_f32_32x32x16_bf16 v[80:95], v[120:123], v[96:99], v[80:95]
	ds_read_b128 v[128:131], v237 offset:49152
	ds_read_b128 v[124:127], v229
	ds_read_b128 v[132:135], v237 offset:57344
	ds_read_b128 v[120:123], v229 offset:1024
	s_waitcnt lgkmcnt(2)
	v_mfma_f32_32x32x16_bf16 v[80:95], v[128:131], v[124:127], v[80:95]
	ds_read_b128 v[162:165], v238 offset:49152
	ds_read_b128 v[128:131], v238 offset:57344
	s_waitcnt lgkmcnt(1)
	v_mfma_f32_32x32x16_bf16 v[80:95], v[162:165], v[120:123], v[80:95]
	v_exp_f32_e32 v163, v66
	v_exp_f32_e32 v164, v67
	v_exp_f32_e32 v167, v70
	v_exp_f32_e32 v184, v71
	v_exp_f32_e32 v187, v74
	v_exp_f32_e32 v160, v64
	v_exp_f32_e32 v188, v75
	v_add_f32_e32 v64, v182, v163
	v_exp_f32_e32 v162, v65
	v_exp_f32_e32 v191, v78
	v_add_f32_e32 v64, 0, v64
	v_add_f32_e32 v65, v180, v164
	v_add_f32_e32 v66, v178, v167
	v_exp_f32_e32 v79, v79
	v_add_f32_e32 v65, 0, v65
	v_add_f32_e32 v64, v66, v64
	v_add_f32_e32 v66, v176, v184
	v_add_f32_e32 v65, v66, v65
	v_add_f32_e32 v66, v174, v187
	v_exp_f32_e32 v165, v68
	v_exp_f32_e32 v166, v69
	v_exp_f32_e32 v185, v72
	v_exp_f32_e32 v186, v73
	v_exp_f32_e32 v189, v76
	v_exp_f32_e32 v190, v77
	v_add_f32_e32 v64, v66, v64
	v_add_f32_e32 v66, v172, v188
	v_add_f32_e32 v65, v66, v65
	v_add_f32_e32 v66, v170, v191
	v_add_f32_e32 v64, v66, v64
	v_add_f32_e32 v66, v168, v79
	v_add_f32_e32 v65, v66, v65
	v_add_f32_e32 v192, v183, v160
	v_add_f32_e32 v193, v181, v162
	v_add_f32_e32 v194, v179, v165
	v_add_f32_e32 v195, v177, v166
	v_add_f32_e32 v196, v175, v185
	v_add_f32_e32 v197, v173, v186
	v_add_f32_e32 v198, v171, v189
	v_add_f32_e32 v199, v169, v190
	v_add_f32_e32 v200, v65, v64
	v_cvt_pk_bf16_f32 v64, v183, v181
	v_cvt_pk_bf16_f32 v65, v182, v180
	v_cvt_pk_bf16_f32 v66, v179, v177
	v_cvt_pk_bf16_f32 v67, v178, v176
	v_cvt_pk_bf16_f32 v68, v175, v173
	v_cvt_pk_bf16_f32 v69, v174, v172
	v_cvt_pk_bf16_f32 v70, v171, v169
	v_cvt_pk_bf16_f32 v71, v170, v168
	s_nop 0
	v_permlane32_swap_b32_e32 v64, v66
	v_permlane32_swap_b32_e32 v65, v67
	v_permlane32_swap_b32_e32 v68, v70
	v_permlane32_swap_b32_e32 v69, v71
	v_cvt_pk_bf16_f32 v72, v160, v162
	v_cvt_pk_bf16_f32 v73, v163, v164
	v_cvt_pk_bf16_f32 v74, v165, v166
	v_cvt_pk_bf16_f32 v75, v167, v184
	v_cvt_pk_bf16_f32 v76, v185, v186
	v_cvt_pk_bf16_f32 v77, v187, v188
	v_cvt_pk_bf16_f32 v78, v189, v190
	v_cvt_pk_bf16_f32 v79, v191, v79
	s_nop 0
	v_permlane32_swap_b32_e32 v72, v74
	v_permlane32_swap_b32_e32 v73, v75
	v_permlane32_swap_b32_e32 v76, v78
	v_permlane32_swap_b32_e32 v77, v79
	ds_read_b64_tr_b16 v[162:163], v228 offset:0
	ds_read_b64_tr_b16 v[164:165], v228 offset:0x800
	ds_read_b64_tr_b16 v[166:167], v228 offset:0x1000
	ds_read_b64_tr_b16 v[168:169], v228 offset:0x1800
	ds_read_b64_tr_b16 v[170:171], v228 offset:0x2000
	ds_read_b64_tr_b16 v[172:173], v228 offset:0x2800
	ds_read_b64_tr_b16 v[174:175], v228 offset:0x3000
	ds_read_b64_tr_b16 v[176:177], v228 offset:0x3800
	s_waitcnt lgkmcnt(0)
	s_nop 0
	v_mfma_f32_32x32x16_bf16 v[0:15], v[64:67], v[162:165], v[0:15]
	ds_read_b64_tr_b16 v[162:163], v228 offset:0x200
	ds_read_b64_tr_b16 v[164:165], v228 offset:0xa00
	v_mfma_f32_32x32x16_bf16 v[0:15], v[68:71], v[166:169], v[0:15]
	ds_read_b64_tr_b16 v[166:167], v228 offset:0x1200
	ds_read_b64_tr_b16 v[168:169], v228 offset:0x1a00
	v_mfma_f32_32x32x16_bf16 v[0:15], v[72:75], v[170:173], v[0:15]
	ds_read_b64_tr_b16 v[170:171], v228 offset:0x2200
	ds_read_b64_tr_b16 v[172:173], v228 offset:0x2a00
	ds_read_b64_tr_b16 v[178:179], v228 offset:0x3200
	ds_read_b64_tr_b16 v[180:181], v228 offset:0x3a00
	s_waitcnt lgkmcnt(0)
	v_mfma_f32_32x32x16_bf16 v[0:15], v[76:79], v[174:177], v[0:15]
	v_mfma_f32_32x32x16_bf16 v[16:31], v[64:67], v[162:165], v[16:31]
	ds_read_b64_tr_b16 v[162:163], v228 offset:0x400
	ds_read_b64_tr_b16 v[164:165], v228 offset:0xc00
	v_mfma_f32_32x32x16_bf16 v[16:31], v[68:71], v[166:169], v[16:31]
	ds_read_b64_tr_b16 v[166:167], v228 offset:0x1400
	ds_read_b64_tr_b16 v[168:169], v228 offset:0x1c00
	v_mfma_f32_32x32x16_bf16 v[16:31], v[72:75], v[170:173], v[16:31]
	ds_read_b64_tr_b16 v[170:171], v228 offset:0x2400
	ds_read_b64_tr_b16 v[172:173], v228 offset:0x2c00
	ds_read_b64_tr_b16 v[174:175], v228 offset:0x3400
	ds_read_b64_tr_b16 v[176:177], v228 offset:0x3c00
	s_waitcnt lgkmcnt(0)
; #define SBAR() __builtin_amdgcn_sched_barrier(0)
; #define WBAR0() do { asm volatile("s_waitcnt vmcnt(0)" ::: "memory"); __syncthreads(); } while (0)
; #define EXPH(P) do { _Pragma("unroll") for (int r = 0; r < 16; ++r) P[r] = __builtin_amdgcn_exp2f(P[r]); } while (0)
; template <int D0> __device__ __forceinline__ void pv_one(f32x16& od, int vb, bf16x8 pa0, bf16x8 pa1, bf16x8 pa2, bf16x8 pa3) {
;     const s16x4 l0 = tr_read<v_rd_off(D0, 0, 0)>(vb), h0 = tr_read<v_rd_off(D0, 0, 1)>(vb), l1 = tr_read<v_rd_off(D0, 1, 0)>(vb), h1 = tr_read<v_rd_off(D0, 1, 1)>(vb);
;     const s16x4 l2 = tr_read<v_rd_off(D0, 2, 0)>(vb), h2 = tr_read<v_rd_off(D0, 2, 1)>(vb), l3 = tr_read<v_rd_off(D0, 3, 0)>(vb), h3 = tr_read<v_rd_off(D0, 3, 1)>(vb);
;     asm volatile("s_waitcnt lgkmcnt(0)" ::: "memory"); SBAR();
;     ...
;     od = __builtin_amdgcn_mfma_f32_32x32x16_bf16(pa0, PK(l0, h0), od, 0, 0, 0);
;     od = __builtin_amdgcn_mfma_f32_32x32x16_bf16(pa1, PK(l1, h1), od, 0, 0, 0);
;     od = __builtin_amdgcn_mfma_f32_32x32x16_bf16(pa2, PK(l2, h2), od, 0, 0, 0);
;     od = __builtin_amdgcn_mfma_f32_32x32x16_bf16(pa3, PK(l3, h3), od, 0, 0, 0);
;     ...
; }
; __device__ __forceinline__ void pv_d0(f32x16* o, int vb, bf16x8 pa0, bf16x8 pa1, bf16x8 pa2, bf16x8 pa3) {
;     pv_one<0>(o[0], vb, pa0, pa1, pa2, pa3); pv_one<1>(o[1], vb, pa0, pa1, pa2, pa3); pv_one<2>(o[2], vb, pa0, pa1, pa2, pa3); pv_one<3>(o[3], vb, pa0, pa1, pa2, pa3);
;     ...
;     pv_d0(o, vb0, pa0, pa1, pa2, pa3);
;     if (!isY) { EXPH(pB0); }
;     WBAR0();
	v_mfma_f32_32x32x16_bf16 v[16:31], v[76:79], v[178:181], v[16:31]
	v_mfma_f32_32x32x16_bf16 v[32:47], v[64:67], v[162:165], v[32:47]
	ds_read_b64_tr_b16 v[162:163], v228 offset:0x600
	ds_read_b64_tr_b16 v[164:165], v228 offset:0xe00
	v_mfma_f32_32x32x16_bf16 v[32:47], v[68:71], v[166:169], v[32:47]
	ds_read_b64_tr_b16 v[166:167], v228 offset:0x1600
	ds_read_b64_tr_b16 v[168:169], v228 offset:0x1e00
	v_mfma_f32_32x32x16_bf16 v[32:47], v[72:75], v[170:173], v[32:47]
	ds_read_b64_tr_b16 v[170:171], v228 offset:0x2600
	ds_read_b64_tr_b16 v[172:173], v228 offset:0x2e00
	ds_read_b64_tr_b16 v[178:179], v228 offset:0x3600
	ds_read_b64_tr_b16 v[180:181], v228 offset:0x3e00
	s_waitcnt lgkmcnt(0)
	v_mfma_f32_32x32x16_bf16 v[32:47], v[76:79], v[174:177], v[32:47]
	v_mfma_f32_32x32x16_bf16 v[48:63], v[64:67], v[162:165], v[48:63]
	s_waitcnt vmcnt(0)
	v_exp_f32_e32 v80, v80
	v_exp_f32_e32 v81, v81
	v_exp_f32_e32 v82, v82
	v_exp_f32_e32 v83, v83
	v_exp_f32_e32 v84, v84
	v_exp_f32_e32 v85, v85
	v_mfma_f32_32x32x16_bf16 v[48:63], v[68:71], v[166:169], v[48:63]
	v_exp_f32_e32 v86, v86
	v_exp_f32_e32 v87, v87
	v_exp_f32_e32 v88, v88
	v_exp_f32_e32 v89, v89
	v_exp_f32_e32 v90, v90
	v_exp_f32_e32 v91, v91
	v_exp_f32_e32 v92, v92
	v_mfma_f32_32x32x16_bf16 v[48:63], v[72:75], v[170:173], v[48:63]
	v_exp_f32_e32 v93, v93
	v_exp_f32_e32 v94, v94
	v_exp_f32_e32 v95, v95
	s_waitcnt lgkmcnt(0)
	s_barrier
; #define SBAR() __builtin_amdgcn_sched_barrier(0)
; #define EXPH(P) do { _Pragma("unroll") for (int r = 0; r < 16; ++r) P[r] = __builtin_amdgcn_exp2f(P[r]); } while (0)
;     ...
;     if (isY) { EXPH(pB0); }
;     SBAR(); finishSM<true>(pB0, pB1, dummy_a, l_reg, pa0, pa1, pa2, pa3); SBAR();
;     pv_d0(o, vb0 + SHM_V, pa0, pa1, pa2, pa3);
;     __builtin_amdgcn_s_setprio(0);
;     (void)dummy_m;
;     { auto rr = __builtin_amdgcn_permlane32_swap(__float_as_uint(l_reg), __float_as_uint(l_reg), false, false); l_reg = __uint_as_float(rr[0]) + __uint_as_float(rr[1]); }
;     {
;         int t2 = threadIdx.x; asm volatile("" : "+v"(t2));
;         const int wid2 = t2 >> 6, lane2 = t2 & 63, r32b = lane2 & 31, hib = lane2 >> 5;
;         float* li2 = (float*)(lds + OFF_WS) + wid2 * 64;
;         if (hib == 0) li2[r32b] = l_reg; asm volatile("s_waitcnt lgkmcnt(0)" ::: "memory");
	v_mfma_f32_32x32x16_bf16 v[48:63], v[76:79], v[178:181], v[48:63]
	v_mfma_f32_32x32x16_bf16 v[64:79], v[144:147], v[116:119], 0
	v_mfma_f32_32x32x16_bf16 v[64:79], v[148:151], v[112:115], v[64:79]
	v_mfma_f32_32x32x16_bf16 v[64:79], v[152:155], v[108:111], v[64:79]
	v_mfma_f32_32x32x16_bf16 v[64:79], v[156:159], v[104:107], v[64:79]
	v_mfma_f32_32x32x16_bf16 v[64:79], v[140:143], v[100:103], v[64:79]
	v_mfma_f32_32x32x16_bf16 v[64:79], v[136:139], v[96:99], v[64:79]
	v_add_f32_e32 v96, 0, v192
	v_add_f32_e32 v97, 0, v193
	v_add_f32_e32 v96, v194, v96
	v_add_f32_e32 v97, v195, v97
	v_add_f32_e32 v96, v196, v96
	v_add_f32_e32 v97, v197, v97
	v_add_f32_e32 v96, v198, v96
	v_mfma_f32_32x32x16_bf16 v[64:79], v[132:135], v[124:127], v[64:79]
	v_add_f32_e32 v97, v199, v97
	v_add_f32_e32 v96, v97, v96
	v_add_f32_e32 v96, v200, v96
	v_add_f32_e32 v96, v230, v96
	v_mfma_f32_32x32x16_bf16 v[64:79], v[128:131], v[120:123], v[64:79]
	s_nop 11
	v_exp_f32_e32 v64, v64
	v_exp_f32_e32 v65, v65
	v_exp_f32_e32 v98, v68
	v_exp_f32_e32 v97, v66
	v_exp_f32_e32 v99, v69
	v_exp_f32_e32 v67, v67
	v_exp_f32_e32 v100, v70
	v_exp_f32_e32 v101, v71
	v_add_f32_e32 v66, v80, v64
	v_exp_f32_e32 v102, v72
	v_add_f32_e32 v66, 0, v66
	v_add_f32_e32 v68, v81, v65
	v_add_f32_e32 v71, v84, v98
	v_exp_f32_e32 v103, v73
	v_add_f32_e32 v68, 0, v68
	v_add_f32_e32 v69, v82, v97
	v_add_f32_e32 v66, v71, v66
	v_add_f32_e32 v71, v85, v99
	v_exp_f32_e32 v104, v74
	v_add_f32_e32 v69, 0, v69
	v_add_f32_e32 v70, v83, v67
	v_add_f32_e32 v68, v71, v68
	v_add_f32_e32 v71, v86, v100
	v_exp_f32_e32 v105, v75
	v_add_f32_e32 v70, 0, v70
	v_add_f32_e32 v69, v71, v69
	v_add_f32_e32 v71, v87, v101
	v_exp_f32_e32 v106, v76
	v_add_f32_e32 v70, v71, v70
	v_add_f32_e32 v71, v88, v102
	v_exp_f32_e32 v107, v77
	v_add_f32_e32 v66, v71, v66
	v_add_f32_e32 v71, v89, v103
	v_exp_f32_e32 v108, v78
	v_add_f32_e32 v68, v71, v68
	v_add_f32_e32 v71, v90, v104
	v_exp_f32_e32 v109, v79
	v_add_f32_e32 v69, v71, v69
	v_add_f32_e32 v71, v91, v105
	v_add_f32_e32 v70, v71, v70
	v_add_f32_e32 v71, v92, v106
	v_add_f32_e32 v66, v71, v66
	v_add_f32_e32 v71, v93, v107
	v_add_f32_e32 v68, v71, v68
	v_add_f32_e32 v71, v94, v108
	v_add_f32_e32 v69, v71, v69
	v_add_f32_e32 v71, v95, v109
	v_add_f32_e32 v70, v71, v70
	v_add_f32_e32 v66, v68, v66
	v_add_f32_e32 v68, v70, v69
	v_add_f32_e32 v66, v68, v66
	v_cvt_pk_bf16_f32 v68, v80, v81
	v_cvt_pk_bf16_f32 v69, v82, v83
	v_cvt_pk_bf16_f32 v70, v84, v85
	v_cvt_pk_bf16_f32 v71, v86, v87
	v_add_f32_e32 v66, v96, v66
	v_permlane32_swap_b32_e32 v68, v70
	v_permlane32_swap_b32_e32 v69, v71
	v_cvt_pk_bf16_f32 v72, v88, v89
	v_cvt_pk_bf16_f32 v73, v90, v91
	v_cvt_pk_bf16_f32 v74, v92, v93
	v_cvt_pk_bf16_f32 v75, v94, v95
	v_cvt_pk_bf16_f32 v76, v64, v65
	v_cvt_pk_bf16_f32 v77, v97, v67
	v_cvt_pk_bf16_f32 v78, v98, v99
	v_cvt_pk_bf16_f32 v79, v100, v101
	v_cvt_pk_bf16_f32 v80, v102, v103
	v_cvt_pk_bf16_f32 v81, v104, v105
	v_cvt_pk_bf16_f32 v82, v106, v107
	v_cvt_pk_bf16_f32 v83, v108, v109
	s_nop 0
	v_permlane32_swap_b32_e32 v72, v74
	v_permlane32_swap_b32_e32 v73, v75
	v_permlane32_swap_b32_e32 v76, v78
	v_permlane32_swap_b32_e32 v77, v79
	v_permlane32_swap_b32_e32 v80, v82
	v_permlane32_swap_b32_e32 v81, v83
	ds_read_b64_tr_b16 v[84:85], v227 offset:0
	ds_read_b64_tr_b16 v[86:87], v227 offset:0x800
	ds_read_b64_tr_b16 v[88:89], v227 offset:0x1000
	ds_read_b64_tr_b16 v[90:91], v227 offset:0x1800
	ds_read_b64_tr_b16 v[92:93], v227 offset:0x2000
	ds_read_b64_tr_b16 v[94:95], v227 offset:0x2800
	ds_read_b64_tr_b16 v[96:97], v227 offset:0x3000
	ds_read_b64_tr_b16 v[98:99], v227 offset:0x3800
	s_waitcnt lgkmcnt(0)
	s_nop 0
	v_mfma_f32_32x32x16_bf16 v[0:15], v[68:71], v[84:87], v[0:15]
	ds_read_b64_tr_b16 v[84:85], v227 offset:0x200
	ds_read_b64_tr_b16 v[86:87], v227 offset:0xa00
	v_mfma_f32_32x32x16_bf16 v[0:15], v[72:75], v[88:91], v[0:15]
	ds_read_b64_tr_b16 v[88:89], v227 offset:0x1200
	ds_read_b64_tr_b16 v[90:91], v227 offset:0x1a00
	v_mfma_f32_32x32x16_bf16 v[0:15], v[76:79], v[92:95], v[0:15]
	ds_read_b64_tr_b16 v[92:93], v227 offset:0x2200
	ds_read_b64_tr_b16 v[94:95], v227 offset:0x2a00
	ds_read_b64_tr_b16 v[100:101], v227 offset:0x3200
	ds_read_b64_tr_b16 v[102:103], v227 offset:0x3a00
	s_waitcnt lgkmcnt(0)
	v_mfma_f32_32x32x16_bf16 v[0:15], v[80:83], v[96:99], v[0:15]
	v_mfma_f32_32x32x16_bf16 v[16:31], v[68:71], v[84:87], v[16:31]
	ds_read_b64_tr_b16 v[84:85], v227 offset:0x400
	ds_read_b64_tr_b16 v[86:87], v227 offset:0xc00
	v_mfma_f32_32x32x16_bf16 v[16:31], v[72:75], v[88:91], v[16:31]
	ds_read_b64_tr_b16 v[88:89], v227 offset:0x1400
	ds_read_b64_tr_b16 v[90:91], v227 offset:0x1c00
	v_mfma_f32_32x32x16_bf16 v[16:31], v[76:79], v[92:95], v[16:31]
	ds_read_b64_tr_b16 v[92:93], v227 offset:0x2400
	ds_read_b64_tr_b16 v[94:95], v227 offset:0x2c00
	ds_read_b64_tr_b16 v[96:97], v227 offset:0x3400
	ds_read_b64_tr_b16 v[98:99], v227 offset:0x3c00
	s_waitcnt lgkmcnt(0)
	v_mfma_f32_32x32x16_bf16 v[16:31], v[80:83], v[100:103], v[16:31]
	v_mfma_f32_32x32x16_bf16 v[32:47], v[68:71], v[84:87], v[32:47]
	ds_read_b64_tr_b16 v[84:85], v227 offset:0x600
	ds_read_b64_tr_b16 v[86:87], v227 offset:0xe00
	v_mfma_f32_32x32x16_bf16 v[32:47], v[72:75], v[88:91], v[32:47]
	ds_read_b64_tr_b16 v[88:89], v227 offset:0x1600
	ds_read_b64_tr_b16 v[90:91], v227 offset:0x1e00
	v_mfma_f32_32x32x16_bf16 v[32:47], v[76:79], v[92:95], v[32:47]
	ds_read_b64_tr_b16 v[92:93], v227 offset:0x2600
	ds_read_b64_tr_b16 v[94:95], v227 offset:0x2e00
	ds_read_b64_tr_b16 v[100:101], v227 offset:0x3600
	ds_read_b64_tr_b16 v[102:103], v227 offset:0x3e00
	s_waitcnt lgkmcnt(0)
	v_mfma_f32_32x32x16_bf16 v[32:47], v[80:83], v[96:99], v[32:47]
	v_mfma_f32_32x32x16_bf16 v[48:63], v[68:71], v[84:87], v[48:63]
	v_mfma_f32_32x32x16_bf16 v[48:63], v[72:75], v[88:91], v[48:63]
	v_mfma_f32_32x32x16_bf16 v[48:63], v[76:79], v[92:95], v[48:63]
	v_mfma_f32_32x32x16_bf16 v[48:63], v[80:83], v[100:103], v[48:63]
	s_setprio 0
	v_mov_b32_e32 v64, v218
	v_mov_b32_e32 v69, v66
	s_nop 1
	v_permlane32_swap_b32_e32 v66, v69
	v_and_b32_e32 v65, 63, v64
	v_and_b32_e32 v68, 0x3fffffc0, v64
	v_and_b32_e32 v67, 31, v64
	v_lshl_add_u32 v68, v68, 2, s50
	v_cmp_gt_u32_e32 vcc, 32, v65
	s_and_saveexec_b64 s[0:1], vcc
	s_cbranch_execz .LBB0_525
	v_add_f32_e32 v66, v66, v69
	v_lshl_add_u32 v69, v67, 2, v68
	ds_write_b32 v69, v66
	s_branch .LBB0_525
